# mla_wq absorbed-weight product on f32 MFMA 16x16x4 instead of VALU loop
# baseline (speedup 1.0000x reference)
.LBB0_854:
	s_add_u32 s0, s34, 0x600000
	s_addc_u32 s1, s35, 0
	v_mov_b32_e32 v50, v181
	s_cmpk_gt_i32 s2, 0xbf
	s_cbranch_scc1 .LBB0_859
	v_lshlrev_b32_e32 v0, 4, v50
	v_and_b32_e32 v0, 0x1f0, v0
	v_mov_b32_e32 v1, 0
	v_and_b32_e32 v43, 0x7f, v50
	s_waitcnt lgkmcnt(0)
	v_lshl_add_u64 v[2:3], s[42:43], 0, v[0:1]
	v_add_u32_e32 v42, 0, v0
	v_lshl_add_u64 v[4:5], s[46:47], 0, v[0:1]
	v_ashrrev_i32_e32 v51, 7, v50
	v_lshlrev_b32_e32 v0, 2, v43
	v_lshl_add_u64 v[6:7], s[44:45], 0, v[0:1]
	v_mul_u32_u24_e32 v0, 0x84, v43
	s_add_i32 s4, 0, 0x14280
	v_lshlrev_b32_e32 v8, 2, v51
	v_add3_u32 v52, s4, v0, v8
	v_and_b32_e32 v0, 31, v50
	v_lshl_add_u32 v44, v0, 2, s4
	v_lshlrev_b32_e32 v0, 1, v0
	v_lshl_add_u64 v[8:9], s[0:1], 0, v[0:1]
	v_add_u32_e32 v0, 0x200, v50
	v_ashrrev_i32_e32 v12, 5, v0
	v_add_u32_e32 v0, 0x400, v50
	v_ashrrev_i32_e32 v18, 5, v0
	v_add_u32_e32 v0, 0x600, v50
	v_ashrrev_i32_e32 v22, 5, v0
	v_add_u32_e32 v0, 0x800, v50
	v_ashrrev_i32_e32 v26, 5, v0
	v_add_u32_e32 v0, 0xa00, v50
	v_ashrrev_i32_e32 v30, 5, v0
	v_add_u32_e32 v0, 0xc00, v50
	v_ashrrev_i32_e32 v10, 5, v50
	v_ashrrev_i32_e32 v34, 5, v0
	v_add_u32_e32 v0, 0xe00, v50
	s_movk_i32 s3, 0x84
	s_movk_i32 s4, 0x204
	v_ashrrev_i32_e32 v11, 31, v10
	v_ashrrev_i32_e32 v38, 5, v0
	v_mul_lo_u32 v45, v10, s3
	v_mul_lo_u32 v46, v10, s4
	v_mul_lo_u32 v47, v12, s4
	v_lshlrev_b64 v[14:15], 14, v[10:11]
	v_ashrrev_i32_e32 v13, 31, v12
	v_ashrrev_i32_e32 v19, 31, v18
	v_mul_lo_u32 v48, v18, s4
	v_ashrrev_i32_e32 v23, 31, v22
	v_mul_lo_u32 v49, v22, s4
	v_ashrrev_i32_e32 v27, 31, v26
	v_mul_lo_u32 v53, v26, s4
	v_ashrrev_i32_e32 v31, 31, v30
	v_mul_lo_u32 v54, v30, s4
	v_ashrrev_i32_e32 v35, 31, v34
	v_mul_lo_u32 v55, v34, s4
	v_ashrrev_i32_e32 v39, 31, v38
	v_mul_lo_u32 v56, v38, s4
	v_mul_lo_u32 v0, v51, s4
	v_mul_lo_u32 v57, v12, s3
	v_mul_lo_u32 v58, v18, s3
	v_mul_lo_u32 v59, v22, s3
	v_mul_lo_u32 v60, v26, s3
	v_mul_lo_u32 v61, v30, s3
	v_mul_lo_u32 v62, v34, s3
	v_mul_lo_u32 v63, v38, s3
	v_mad_u32_u24 v11, v43, s4, 0
	v_lshlrev_b64 v[16:17], 14, v[12:13]
	v_lshlrev_b64 v[20:21], 14, v[18:19]
	v_lshlrev_b64 v[24:25], 14, v[22:23]
	v_lshlrev_b64 v[28:29], 14, v[26:27]
	v_lshlrev_b64 v[32:33], 14, v[30:31]
	v_lshlrev_b64 v[36:37], 14, v[34:35]
	v_lshlrev_b64 v[40:41], 14, v[38:39]
	v_add_u32_e32 v0, 0, v0
	v_add_u32_e32 v11, 0x4080, v11
	s_movk_i32 s3, 0x3000
	v_add_u32_e32 v13, v42, v46
	v_add_u32_e32 v19, v42, v47
	v_add_u32_e32 v23, v42, v48
	v_add_u32_e32 v27, v42, v49
	v_add_u32_e32 v31, v42, v53
	v_add_u32_e32 v35, v42, v54
	v_add_u32_e32 v39, v42, v55
	v_add_u32_e32 v53, v42, v56
	v_add_u32_e32 v54, v44, v45
	s_movk_i32 s8, 0x300
	v_add_u32_e32 v55, v44, v57
	v_add_u32_e32 v56, v44, v58
	v_add_u32_e32 v57, v44, v59
	v_add_u32_e32 v58, v44, v60
	v_add_u32_e32 v59, v44, v61
	v_add_u32_e32 v60, v44, v62
	v_add_u32_e32 v61, v44, v63
	s_mov_b32 s9, s2
	v_and_b32_e32 v169, 15, v50
	v_bfe_u32 v176, v50, 4, 2
	v_lshrrev_b32_e32 v177, 6, v50
	v_mul_u32_u24_e32 v165, 0x204, v169
	v_lshl_add_u32 v165, v176, 2, v165
	v_mul_u32_u24_e32 v164, 0x2040, v177
	v_add_u32_e32 v164, v164, v165
	v_add_u32_e32 v164, 0x4080, v164
	v_mul_u32_u24_e32 v166, 0x840, v177
	v_mul_u32_u24_e32 v167, 0x210, v176
	v_add_u32_e32 v166, v166, v167
	v_add_u32_e32 v166, 0x14280, v166
	v_lshl_add_u32 v166, v169, 2, v166
	v_lshlrev_b32_e32 v167, 6, v177
	v_lshl_add_u32 v167, v176, 4, v167
	v_lshlrev_b32_e32 v168, 2, v169

.LBB0_857:
	s_lshl_b32 s5, s4, 2
	v_add_u32_e32 v169, s5, v168
	global_load_dword v170, v167, s[44:45]
	global_load_dword v171, v167, s[44:45] offset:4
	global_load_dword v172, v167, s[44:45] offset:8
	global_load_dword v173, v167, s[44:45] offset:12
	global_load_dword v174, v169, s[40:41]
	global_load_dword v175, v169, s[40:41] offset:64
	ds_read_b32 v152, v164
	ds_read_b32 v153, v165
	ds_read_b32 v154, v165 offset:8256
	ds_read_b32 v155, v164 offset:16
	ds_read_b32 v156, v165 offset:16
	ds_read_b32 v157, v165 offset:8272
	ds_read_b32 v158, v164 offset:32
	ds_read_b32 v159, v165 offset:32
	ds_read_b32 v160, v165 offset:8288
	ds_read_b32 v161, v164 offset:48
	ds_read_b32 v162, v165 offset:48
	ds_read_b32 v163, v165 offset:8304
	s_waitcnt lgkmcnt(6)
	v_mfma_f32_16x16x4_f32 v[144:147], v152, v153, 0
	v_mfma_f32_16x16x4_f32 v[148:151], v152, v154, 0
	v_mfma_f32_16x16x4_f32 v[144:147], v155, v156, v[144:147]
	v_mfma_f32_16x16x4_f32 v[148:151], v155, v157, v[148:151]
	ds_read_b32 v152, v164 offset:64
	ds_read_b32 v153, v165 offset:64
	ds_read_b32 v154, v165 offset:8320
	ds_read_b32 v155, v164 offset:80
	ds_read_b32 v156, v165 offset:80
	ds_read_b32 v157, v165 offset:8336
	s_waitcnt lgkmcnt(6)
	v_mfma_f32_16x16x4_f32 v[144:147], v158, v159, v[144:147]
	v_mfma_f32_16x16x4_f32 v[148:151], v158, v160, v[148:151]
	v_mfma_f32_16x16x4_f32 v[144:147], v161, v162, v[144:147]
	v_mfma_f32_16x16x4_f32 v[148:151], v161, v163, v[148:151]
	ds_read_b32 v158, v164 offset:96
	ds_read_b32 v159, v165 offset:96
	ds_read_b32 v160, v165 offset:8352
	ds_read_b32 v161, v164 offset:112
	ds_read_b32 v162, v165 offset:112
	ds_read_b32 v163, v165 offset:8368
	s_waitcnt lgkmcnt(6)
	v_mfma_f32_16x16x4_f32 v[144:147], v152, v153, v[144:147]
	v_mfma_f32_16x16x4_f32 v[148:151], v152, v154, v[148:151]
	v_mfma_f32_16x16x4_f32 v[144:147], v155, v156, v[144:147]
	v_mfma_f32_16x16x4_f32 v[148:151], v155, v157, v[148:151]
	ds_read_b32 v152, v164 offset:128
	ds_read_b32 v153, v165 offset:128
	ds_read_b32 v154, v165 offset:8384
	ds_read_b32 v155, v164 offset:144
	ds_read_b32 v156, v165 offset:144
	ds_read_b32 v157, v165 offset:8400
	s_waitcnt lgkmcnt(6)
	v_mfma_f32_16x16x4_f32 v[144:147], v158, v159, v[144:147]
	v_mfma_f32_16x16x4_f32 v[148:151], v158, v160, v[148:151]
	v_mfma_f32_16x16x4_f32 v[144:147], v161, v162, v[144:147]
	v_mfma_f32_16x16x4_f32 v[148:151], v161, v163, v[148:151]
	ds_read_b32 v158, v164 offset:160
	ds_read_b32 v159, v165 offset:160
	ds_read_b32 v160, v165 offset:8416
	ds_read_b32 v161, v164 offset:176
	ds_read_b32 v162, v165 offset:176
	ds_read_b32 v163, v165 offset:8432
	s_waitcnt lgkmcnt(6)
	v_mfma_f32_16x16x4_f32 v[144:147], v152, v153, v[144:147]
	v_mfma_f32_16x16x4_f32 v[148:151], v152, v154, v[148:151]
	v_mfma_f32_16x16x4_f32 v[144:147], v155, v156, v[144:147]
	v_mfma_f32_16x16x4_f32 v[148:151], v155, v157, v[148:151]
	ds_read_b32 v152, v164 offset:192
	ds_read_b32 v153, v165 offset:192
	ds_read_b32 v154, v165 offset:8448
	ds_read_b32 v155, v164 offset:208
	ds_read_b32 v156, v165 offset:208
	ds_read_b32 v157, v165 offset:8464
	s_waitcnt lgkmcnt(6)
	v_mfma_f32_16x16x4_f32 v[144:147], v158, v159, v[144:147]
	v_mfma_f32_16x16x4_f32 v[148:151], v158, v160, v[148:151]
	v_mfma_f32_16x16x4_f32 v[144:147], v161, v162, v[144:147]
	v_mfma_f32_16x16x4_f32 v[148:151], v161, v163, v[148:151]
	ds_read_b32 v158, v164 offset:224
	ds_read_b32 v159, v165 offset:224
	ds_read_b32 v160, v165 offset:8480
	ds_read_b32 v161, v164 offset:240
	ds_read_b32 v162, v165 offset:240
	ds_read_b32 v163, v165 offset:8496
	s_waitcnt lgkmcnt(6)
	v_mfma_f32_16x16x4_f32 v[144:147], v152, v153, v[144:147]
	v_mfma_f32_16x16x4_f32 v[148:151], v152, v154, v[148:151]
	v_mfma_f32_16x16x4_f32 v[144:147], v155, v156, v[144:147]
	v_mfma_f32_16x16x4_f32 v[148:151], v155, v157, v[148:151]
	ds_read_b32 v152, v164 offset:256
	ds_read_b32 v153, v165 offset:256
	ds_read_b32 v154, v165 offset:8512
	ds_read_b32 v155, v164 offset:272
	ds_read_b32 v156, v165 offset:272
	ds_read_b32 v157, v165 offset:8528
	s_waitcnt lgkmcnt(6)
	v_mfma_f32_16x16x4_f32 v[144:147], v158, v159, v[144:147]
	v_mfma_f32_16x16x4_f32 v[148:151], v158, v160, v[148:151]
	v_mfma_f32_16x16x4_f32 v[144:147], v161, v162, v[144:147]
	v_mfma_f32_16x16x4_f32 v[148:151], v161, v163, v[148:151]
	ds_read_b32 v158, v164 offset:288
	ds_read_b32 v159, v165 offset:288
	ds_read_b32 v160, v165 offset:8544
	ds_read_b32 v161, v164 offset:304
	ds_read_b32 v162, v165 offset:304
	ds_read_b32 v163, v165 offset:8560
	s_waitcnt lgkmcnt(6)
	v_mfma_f32_16x16x4_f32 v[144:147], v152, v153, v[144:147]
	v_mfma_f32_16x16x4_f32 v[148:151], v152, v154, v[148:151]
	v_mfma_f32_16x16x4_f32 v[144:147], v155, v156, v[144:147]
	v_mfma_f32_16x16x4_f32 v[148:151], v155, v157, v[148:151]
	ds_read_b32 v152, v164 offset:320
	ds_read_b32 v153, v165 offset:320
	ds_read_b32 v154, v165 offset:8576
	ds_read_b32 v155, v164 offset:336
	ds_read_b32 v156, v165 offset:336
	ds_read_b32 v157, v165 offset:8592
	s_waitcnt lgkmcnt(6)
	v_mfma_f32_16x16x4_f32 v[144:147], v158, v159, v[144:147]
	v_mfma_f32_16x16x4_f32 v[148:151], v158, v160, v[148:151]
	v_mfma_f32_16x16x4_f32 v[144:147], v161, v162, v[144:147]
	v_mfma_f32_16x16x4_f32 v[148:151], v161, v163, v[148:151]
	ds_read_b32 v158, v164 offset:352
	ds_read_b32 v159, v165 offset:352
	ds_read_b32 v160, v165 offset:8608
	ds_read_b32 v161, v164 offset:368
	ds_read_b32 v162, v165 offset:368
	ds_read_b32 v163, v165 offset:8624
	s_waitcnt lgkmcnt(6)
	v_mfma_f32_16x16x4_f32 v[144:147], v152, v153, v[144:147]
	v_mfma_f32_16x16x4_f32 v[148:151], v152, v154, v[148:151]
	v_mfma_f32_16x16x4_f32 v[144:147], v155, v156, v[144:147]
	v_mfma_f32_16x16x4_f32 v[148:151], v155, v157, v[148:151]
	ds_read_b32 v152, v164 offset:384
	ds_read_b32 v153, v165 offset:384
	ds_read_b32 v154, v165 offset:8640
	ds_read_b32 v155, v164 offset:400
	ds_read_b32 v156, v165 offset:400
	ds_read_b32 v157, v165 offset:8656
	s_waitcnt lgkmcnt(6)
	v_mfma_f32_16x16x4_f32 v[144:147], v158, v159, v[144:147]
	v_mfma_f32_16x16x4_f32 v[148:151], v158, v160, v[148:151]
	v_mfma_f32_16x16x4_f32 v[144:147], v161, v162, v[144:147]
	v_mfma_f32_16x16x4_f32 v[148:151], v161, v163, v[148:151]
	ds_read_b32 v158, v164 offset:416
	ds_read_b32 v159, v165 offset:416
	ds_read_b32 v160, v165 offset:8672
	ds_read_b32 v161, v164 offset:432
	ds_read_b32 v162, v165 offset:432
	ds_read_b32 v163, v165 offset:8688
	s_waitcnt lgkmcnt(6)
	v_mfma_f32_16x16x4_f32 v[144:147], v152, v153, v[144:147]
	v_mfma_f32_16x16x4_f32 v[148:151], v152, v154, v[148:151]
	v_mfma_f32_16x16x4_f32 v[144:147], v155, v156, v[144:147]
	v_mfma_f32_16x16x4_f32 v[148:151], v155, v157, v[148:151]
	ds_read_b32 v152, v164 offset:448
	ds_read_b32 v153, v165 offset:448
	ds_read_b32 v154, v165 offset:8704
	ds_read_b32 v155, v164 offset:464
	ds_read_b32 v156, v165 offset:464
	ds_read_b32 v157, v165 offset:8720
	s_waitcnt lgkmcnt(6)
	v_mfma_f32_16x16x4_f32 v[144:147], v158, v159, v[144:147]
	v_mfma_f32_16x16x4_f32 v[148:151], v158, v160, v[148:151]
	v_mfma_f32_16x16x4_f32 v[144:147], v161, v162, v[144:147]
	v_mfma_f32_16x16x4_f32 v[148:151], v161, v163, v[148:151]
	ds_read_b32 v158, v164 offset:480
	ds_read_b32 v159, v165 offset:480
	ds_read_b32 v160, v165 offset:8736
	ds_read_b32 v161, v164 offset:496
	ds_read_b32 v162, v165 offset:496
	ds_read_b32 v163, v165 offset:8752
	s_waitcnt lgkmcnt(6)
	v_mfma_f32_16x16x4_f32 v[144:147], v152, v153, v[144:147]
	v_mfma_f32_16x16x4_f32 v[148:151], v152, v154, v[148:151]
	v_mfma_f32_16x16x4_f32 v[144:147], v155, v156, v[144:147]
	v_mfma_f32_16x16x4_f32 v[148:151], v155, v157, v[148:151]
	s_waitcnt lgkmcnt(0)
	v_mfma_f32_16x16x4_f32 v[144:147], v158, v159, v[144:147]
	v_mfma_f32_16x16x4_f32 v[148:151], v158, v160, v[148:151]
	v_mfma_f32_16x16x4_f32 v[144:147], v161, v162, v[144:147]
	v_mfma_f32_16x16x4_f32 v[148:151], v161, v163, v[148:151]
	s_movk_i32 s5, 0x200
	s_nop 7
	s_nop 7
	s_waitcnt vmcnt(0)
	v_mul_f32_e32 v176, v144, v170
	v_mul_f32_e32 v176, v176, v174
	ds_write_b32 v166, v176
	v_mul_f32_e32 v176, v145, v171
	v_mul_f32_e32 v176, v176, v174
	ds_write_b32 v166, v176 offset:132
	v_mul_f32_e32 v176, v146, v172
	v_mul_f32_e32 v176, v176, v174
	ds_write_b32 v166, v176 offset:264
	v_mul_f32_e32 v176, v147, v173
	v_mul_f32_e32 v176, v176, v174
	ds_write_b32 v166, v176 offset:396
	v_mul_f32_e32 v176, v148, v170
	v_mul_f32_e32 v176, v176, v175
	ds_write_b32 v166, v176 offset:64
	v_mul_f32_e32 v176, v149, v171
	v_mul_f32_e32 v176, v176, v175
	ds_write_b32 v166, v176 offset:196
	v_mul_f32_e32 v176, v150, v172
	v_mul_f32_e32 v176, v176, v175
	ds_write_b32 v166, v176 offset:328
	v_mul_f32_e32 v176, v151, v173
	v_mul_f32_e32 v176, v176, v175
	ds_write_b32 v166, v176 offset:460
	s_ashr_i32 s5, s4, 31
	v_add_u32_e32 v64, s6, v10
	s_add_i32 s9, s9, s82
	v_lshl_add_u64 v[62:63], s[4:5], 1, v[8:9]
	v_add_u32_e32 v66, s6, v12
	v_add_u32_e32 v68, s6, v18
	v_add_u32_e32 v70, s6, v22
	v_add_u32_e32 v72, s6, v26
	v_add_u32_e32 v74, s6, v30
	v_add_u32_e32 v76, s6, v34
	v_add_u32_e32 v87, s6, v38
	s_cmpk_gt_i32 s9, 0xbf
	v_mad_i64_i32 v[64:65], s[4:5], v64, s8, v[62:63]
	v_mad_i64_i32 v[66:67], s[4:5], v66, s8, v[62:63]
	v_mad_i64_i32 v[68:69], s[4:5], v68, s8, v[62:63]
	v_mad_i64_i32 v[70:71], s[4:5], v70, s8, v[62:63]
	v_mad_i64_i32 v[72:73], s[4:5], v72, s8, v[62:63]
	v_mad_i64_i32 v[74:75], s[4:5], v74, s8, v[62:63]
	v_mad_i64_i32 v[76:77], s[4:5], v76, s8, v[62:63]
	v_mad_i64_i32 v[62:63], s[4:5], v87, s8, v[62:63]
	s_waitcnt lgkmcnt(0)
	s_barrier
	ds_read_b32 v42, v54
	ds_read_b32 v43, v55
	ds_read_b32 v44, v56
	ds_read_b32 v45, v57
	ds_read_b32 v46, v58
	ds_read_b32 v47, v59
	ds_read_b32 v48, v60
	ds_read_b32 v49, v61
	s_waitcnt lgkmcnt(7)
	v_cvt_pk_bf16_f32 v42, v42, s0
	s_waitcnt lgkmcnt(6)
	v_cvt_pk_bf16_f32 v43, v43, s0
	s_waitcnt lgkmcnt(5)
	v_cvt_pk_bf16_f32 v44, v44, s0
	s_waitcnt lgkmcnt(4)
	v_cvt_pk_bf16_f32 v45, v45, s0
	s_waitcnt lgkmcnt(3)
	v_cvt_pk_bf16_f32 v46, v46, s0
	s_waitcnt lgkmcnt(2)
	v_cvt_pk_bf16_f32 v47, v47, s0
	s_waitcnt lgkmcnt(1)
	v_cvt_pk_bf16_f32 v48, v48, s0
	s_waitcnt lgkmcnt(0)
	v_cvt_pk_bf16_f32 v49, v49, s0
	global_store_short v[64:65], v42, off
	global_store_short v[66:67], v43, off
	global_store_short v[68:69], v44, off
	global_store_short v[70:71], v45, off
	global_store_short v[72:73], v46, off
	global_store_short v[74:75], v47, off
	global_store_short v[76:77], v48, off
	global_store_short v[62:63], v49, off
	s_cbranch_scc0 .LBB0_856
